# first layer phase 0: one rmsnorm iteration inside each of the first four weight-transpose rounds (body renamed to v64+), bandwidth-bound and latency-bound work overlapped
# speedup vs baseline: 1.0073x; 1.0073x over previous
; DI int tidx() { int t = threadIdx.x; asm volatile("" : "+v"(t)); return t; }
; DI int bidx() { int b = blockIdx.x; asm volatile("" : "+s"(b)); return b; }
; DI void rmsnorm_rows(const float* x, const float* g, bf16_t* outb, float* outf) {
;   const int lane = tidx() & 63, w = tidx() >> 6;
;   for (int it = bidx(); it < NTOK / 16; it += gridDim.x) {
;     float4 v[2][4]; float ss[2] = {0.f, 0.f};
; #pragma unroll
;     for (int rr = 0; rr < 2; ++rr) {
;       const float* xr = x + (size_t)(it * 16 + rr * 8 + w) * 1024;
; #pragma unroll
;       for (int i = 0; i < 4; ++i) v[rr][i] = *(const float4*)(xr + lane * 4 + 256 * i);
; DI void phase0(const Params& p, int l, char* smraw) {
;   const int half = tidx() >> 8, ltid = tidx() & 255;
;   float* tile = (float*)(smraw + half * 17408);
;   {
;     int id0 = bidx() * 2;
;     TrTile cur = tr_find(p, l, id0 + half);
;     float4 rg[4];
;     tr_load(cur, ltid, rg);
.Lfz_no2:
.LBB0_20:
	s_xor_b64 s[0:1], s[2:3], -1
	v_writelane_b32 v252, s0, 50
	v_mov_b32_e32 v0, v201
	v_mov_b32_e32 v24, v201
	v_writelane_b32 v252, s1, 51
	s_movk_i32 s0, 0x94c
	v_readlane_b32 s22, v252, 4
	v_ashrrev_i32_e32 v36, 8, v0
	s_lshl_b32 s60, s22, 1
	v_add_u32_e32 v0, s60, v36
	v_cmp_gt_i32_e64 s[42:43], s0, v0
	v_readlane_b32 s0, v252, 6
	v_readlane_b32 s1, v252, 7
	s_mov_b64 s[2:3], s[0:1]
	s_mov_b64 s[2:3], s[0:1]
	s_mov_b32 s1, s89
	s_mul_i32 s0, s4, 0x6a6000
	s_xor_b64 s[12:13], s[8:9], -1
	v_cndmask_b32_e64 v0, 0, v0, s[42:43]
	s_lshl_b32 s2, s4, 14
	s_mov_b32 s3, s89
	s_lshl_b32 s34, s4, 13
	s_mov_b32 s35, s89
	s_lshl_b32 s36, s4, 18
	s_mov_b32 s37, s89
	s_lshl_b32 s38, s4, 20
	s_mov_b32 s39, s89
	s_mov_b32 s68, s4
	s_cmp_eq_u32 s68, 0
	s_cbranch_scc0 .Lrn_nopro
	v_readlane_b32 s94, v252, 6
	v_readlane_b32 s95, v252, 7
	s_load_dwordx2 s[96:97], s[94:95], 0x0
	s_load_dwordx2 s[98:99], s[94:95], 0x8
	s_load_dwordx2 s[100:101], s[94:95], 0xf0
	v_and_b32_e32 v124, 63, v201
	v_lshlrev_b32_e32 v126, 4, v124
	v_mov_b32_e32 v127, 0
	v_readlane_b32 s93, v252, 4
	v_readlane_b32 s86, v252, 45
	s_mov_b32 s85, 0x800000
	s_mov_b32 s88, 0
	v_lshrrev_b32_e32 v120, 6, v201
	v_lshl_add_u32 v120, s93, 4, v120
	s_waitcnt lgkmcnt(0)
	v_lshl_add_u64 v[114:115], s[96:97], 0, v[126:127]
	v_lshl_add_u64 v[116:117], s[98:99], 0, v[126:127]
	v_lshlrev_b32_e32 v126, 3, v124
	s_add_u32 s100, s100, 0x12a4500
	s_addc_u32 s101, s101, 0
	v_lshl_add_u64 v[118:119], s[100:101], 0, v[126:127]
.Lrn_nopro:
	s_lshl_b32 s40, s4, 19
	s_mov_b32 s41, s89
	s_mov_b64 s[44:45], 0
	v_writelane_b32 v252, s0, 52
	s_mov_b32 s23, s1
	s_nop 0
	v_writelane_b32 v252, s1, 53
	s_branch .LBB0_22

; DI int bidx() { int b = blockIdx.x; asm volatile("" : "+s"(b)); return b; }
; DI float wave_sum_fast(float v) { v = fdpp_add(v, 0); v = fdpp_add(v, 1); v = fdpp_add(v, 2); v = fdpp_add(v, 3); v = xor16_sum(v); return xor32_sum(v); }
; DI void rmsnorm_rows(const float* x, const float* g, bf16_t* outb, float* outf) {
;     ...
;   for (int it = bidx(); it < NTOK / 16; it += gridDim.x) {
;     float4 v[2][4]; float ss[2] = {0.f, 0.f};
; #pragma unroll
;     for (int rr = 0; rr < 2; ++rr) {
;       const float* xr = x + (size_t)(it * 16 + rr * 8 + w) * 1024;
; #pragma unroll
;       for (int i = 0; i < 4; ++i) v[rr][i] = *(const float4*)(xr + lane * 4 + 256 * i);
;     }
;     float4 gg[4];
; #pragma unroll
;     for (int i = 0; i < 4; ++i) gg[i] = *(const float4*)(g + lane * 4 + 256 * i);
; #pragma unroll
;     for (int rr = 0; rr < 2; ++rr) {
; #pragma unroll
;       for (int i = 0; i < 4; ++i) ss[rr] += v[rr][i].x * v[rr][i].x + v[rr][i].y * v[rr][i].y + v[rr][i].z * v[rr][i].z + v[rr][i].w * v[rr][i].w;
;       ss[rr] = wave_sum_fast(ss[rr]);
;     }
; #pragma unroll
;     for (int rr = 0; rr < 2; ++rr) {
;       const int row = it * 16 + rr * 8 + w;
;       const float rs = rsqrtf(ss[rr] * (1.f / 1024.f) + 1e-6f);
.LBB0_139:
	s_cmp_eq_u32 s68, 0
	s_cbranch_scc0 .Lrn_done
	s_cmp_lt_u32 s88, 4
	s_cbranch_scc0 .Lrn_done
	v_ashrrev_i32_e32 v121, 31, v120
	v_lshlrev_b64 v[66:67], 12, v[120:121]
	v_lshl_add_u64 v[70:71], v[114:115], 0, v[66:67]
	global_load_dwordx4 v[78:81], v[70:71], off
	global_load_dwordx4 v[86:89], v[70:71], off offset:1024
	global_load_dwordx4 v[66:69], v[70:71], off offset:2048
	s_nop 0
	global_load_dwordx4 v[70:73], v[70:71], off offset:3072
	v_add_u32_e32 v122, 8, v120
	v_ashrrev_i32_e32 v123, 31, v122
	v_lshlrev_b64 v[74:75], 12, v[122:123]
	v_lshl_add_u64 v[74:75], v[114:115], 0, v[74:75]
	global_load_dwordx4 v[102:105], v[74:75], off
	global_load_dwordx4 v[94:97], v[74:75], off offset:1024
	global_load_dwordx4 v[90:93], v[74:75], off offset:2048
	s_nop 0
	global_load_dwordx4 v[74:77], v[74:75], off offset:3072
	s_nop 0
	global_load_dwordx4 v[110:113], v[116:117], off
	global_load_dwordx4 v[106:109], v[116:117], off offset:1024
	global_load_dwordx4 v[98:101], v[116:117], off offset:2048
	global_load_dwordx4 v[82:85], v[116:117], off offset:3072
	v_lshlrev_b64 v[124:125], 11, v[120:121]
	s_mov_b32 s84, 0x3a800000
	v_lshl_add_u64 v[124:125], v[118:119], 0, v[124:125]
	v_lshlrev_b64 v[122:123], 11, v[122:123]
	v_lshl_add_u64 v[122:123], v[118:119], 0, v[122:123]
	v_add_u32_e32 v120, s86, v120
	s_waitcnt vmcnt(11)
	v_pk_mul_f32 v[128:129], v[78:79], v[78:79]
	s_waitcnt vmcnt(10)
	v_pk_mul_f32 v[132:133], v[86:87], v[86:87]
	v_pk_mul_f32 v[126:127], v[80:81], v[80:81]
	s_waitcnt vmcnt(8)
	v_pk_mul_f32 v[136:137], v[70:71], v[70:71]
	v_pk_mul_f32 v[130:131], v[88:89], v[88:89]
	v_pk_mul_f32 v[134:135], v[66:67], v[66:67]
	v_pk_mul_f32 v[140:141], v[72:73], v[72:73]
	v_add_f32_e32 v64, v132, v133
	v_add_f32_e32 v121, v128, v129
	v_add_f32_e32 v151, v136, v137
	s_waitcnt vmcnt(7)
	v_pk_mul_f32 v[128:129], v[102:103], v[102:103]
	s_waitcnt vmcnt(6)
	v_pk_mul_f32 v[132:133], v[94:95], v[94:95]
	v_add_f32_e32 v150, v134, v135
	s_waitcnt vmcnt(5)
	v_pk_mul_f32 v[134:135], v[90:91], v[90:91]
	v_pk_mul_f32 v[142:143], v[104:105], v[104:105]
	v_pk_mul_f32 v[144:145], v[96:97], v[96:97]
	v_add_f32_e32 v132, v132, v133
	v_add_f32_e32 v128, v128, v129
	v_add_f32_e32 v64, v64, v130
	v_add_f32_e32 v121, v121, v126
	v_add_f32_e32 v130, v151, v140
	v_pk_mul_f32 v[138:139], v[68:69], v[68:69]
	s_waitcnt vmcnt(4)
	v_pk_mul_f32 v[136:137], v[74:75], v[74:75]
	v_pk_mul_f32 v[146:147], v[92:93], v[92:93]
	v_add_f32_e32 v129, v134, v135
	v_add_f32_e32 v64, v64, v131
	v_add_f32_e32 v121, v121, v127
	v_add_f32_e32 v127, v130, v141
	v_add_f32_e32 v130, v132, v144
	v_add_f32_e32 v128, v128, v142
	v_pk_mul_f32 v[148:149], v[76:77], v[76:77]
	v_add_f32_e32 v133, v136, v137
	v_add_f32_e32 v126, v150, v138
	v_add_f32_e32 v129, v129, v146
	v_add_f32_e32 v130, v130, v145
	v_add_f32_e32 v64, v121, v64
	v_add_f32_e32 v121, v128, v143
	v_add_f32_e32 v126, v126, v139
	v_add_f32_e32 v131, v133, v148
	v_add_f32_e32 v128, v129, v147
	v_add_f32_e32 v121, v121, v130
	v_add_f32_e32 v129, v131, v149
	v_add_f32_e32 v64, v64, v126
	v_add_f32_e32 v121, v121, v128
	v_add_f32_e32 v64, v64, v127
	v_add_f32_e32 v121, v121, v129
	s_nop 0
	v_add_f32_dpp v64, v64, v64 quad_perm:[1,0,3,2] row_mask:0xf bank_mask:0xf bound_ctrl:1
	v_add_f32_dpp v121, v121, v121 quad_perm:[1,0,3,2] row_mask:0xf bank_mask:0xf bound_ctrl:1
	s_nop 0
	v_add_f32_dpp v64, v64, v64 quad_perm:[2,3,0,1] row_mask:0xf bank_mask:0xf bound_ctrl:1
	v_add_f32_dpp v121, v121, v121 quad_perm:[2,3,0,1] row_mask:0xf bank_mask:0xf bound_ctrl:1
	s_nop 0
	v_add_f32_dpp v64, v64, v64 row_half_mirror row_mask:0xf bank_mask:0xf bound_ctrl:1
	v_add_f32_dpp v121, v121, v121 row_half_mirror row_mask:0xf bank_mask:0xf bound_ctrl:1
	s_nop 0
	v_add_f32_dpp v64, v64, v64 row_mirror row_mask:0xf bank_mask:0xf bound_ctrl:1
	v_add_f32_dpp v121, v121, v121 row_mirror row_mask:0xf bank_mask:0xf bound_ctrl:1
	v_mov_b32_e32 v126, v64
	v_mov_b32_e32 v128, v121
	s_nop 0
	v_permlane16_swap_b32_e32 v64, v126
	v_permlane16_swap_b32_e32 v121, v128
	v_add_f32_e32 v127, v64, v126
	v_add_f32_e32 v126, v121, v128
	v_mov_b32_e32 v129, v127
	v_mov_b32_e32 v128, v126
	s_nop 0
	v_permlane32_swap_b32_e32 v127, v129
	v_permlane32_swap_b32_e32 v126, v128
	v_pk_add_f32 v[126:127], v[126:127], v[128:129]
	s_nop 0
	v_pk_fma_f32 v[126:127], v[126:127], s[84:85], v[200:201] op_sel_hi:[1,0,0]
	s_nop 0
	v_mul_f32_e32 v64, 0x4b800000, v127
	v_cmp_gt_f32_e32 vcc, s85, v127
	s_nop 1
	v_cndmask_b32_e32 v64, v127, v64, vcc
	v_rsq_f32_e32 v64, v64
	s_nop 0
	v_mul_f32_e32 v121, 0x45800000, v64
	v_cndmask_b32_e32 v64, v64, v121, vcc
	v_pk_mul_f32 v[66:67], v[66:67], v[64:65] op_sel_hi:[1,0]
	v_pk_mul_f32 v[68:69], v[68:69], v[64:65] op_sel_hi:[1,0]
	s_waitcnt vmcnt(1)
; DI unsigned pack2(float a, float b) { fv2 v = {a, b}; return __builtin_bit_cast(unsigned, __builtin_convertvector(v, bfv2)); }
; DI void rmsnorm_rows(const float* x, const float* g, bf16_t* outb, float* outf) {
;     ...
;     for (int rr = 0; rr < 2; ++rr) {
;       const int row = it * 16 + rr * 8 + w;
;       const float rs = rsqrtf(ss[rr] * (1.f / 1024.f) + 1e-6f);
; #pragma unroll
;       for (int i = 0; i < 4; ++i) {
;         const float o0 = v[rr][i].x * rs * gg[i].x, o1 = v[rr][i].y * rs * gg[i].y, o2 = v[rr][i].z * rs * gg[i].z, o3 = v[rr][i].w * rs * gg[i].w;
;         if (outf) { *(float4*)(outf + (size_t)row * 1024 + lane * 4 + 256 * i) = make_float4(o0, o1, o2, o3); }
;         else { uint2 o; o.x = pack2(o0, o1); o.y = pack2(o2, o3); *(uint2*)(outb + (size_t)row * 1024 + lane * 4 + 256 * i) = o; }
;       }
	v_pk_mul_f32 v[66:67], v[98:99], v[66:67]
	v_pk_mul_f32 v[68:69], v[100:101], v[68:69]
	v_pk_mul_f32 v[78:79], v[78:79], v[64:65] op_sel_hi:[1,0]
	v_pk_mul_f32 v[80:81], v[80:81], v[64:65] op_sel_hi:[1,0]
	v_pk_mul_f32 v[86:87], v[86:87], v[64:65] op_sel_hi:[1,0]
	v_pk_mul_f32 v[88:89], v[88:89], v[64:65] op_sel_hi:[1,0]
	v_cvt_pk_bf16_f32 v66, v66, v67
	v_cvt_pk_bf16_f32 v67, v68, v69
	v_pk_mul_f32 v[68:69], v[70:71], v[64:65] op_sel_hi:[1,0]
	v_pk_mul_f32 v[70:71], v[72:73], v[64:65] op_sel_hi:[1,0]
	v_mul_f32_e32 v64, 0x4b800000, v126
	v_cmp_gt_f32_e32 vcc, s85, v126
	v_pk_mul_f32 v[78:79], v[110:111], v[78:79]
	v_pk_mul_f32 v[80:81], v[112:113], v[80:81]
	v_cndmask_b32_e32 v64, v126, v64, vcc
	v_rsq_f32_e32 v64, v64
	v_pk_mul_f32 v[86:87], v[106:107], v[86:87]
	v_pk_mul_f32 v[88:89], v[108:109], v[88:89]
	v_cvt_pk_bf16_f32 v78, v78, v79
	v_cvt_pk_bf16_f32 v79, v80, v81
	v_cvt_pk_bf16_f32 v80, v86, v87
	v_cvt_pk_bf16_f32 v81, v88, v89
	s_waitcnt vmcnt(0)
	v_pk_mul_f32 v[68:69], v[82:83], v[68:69]
	v_pk_mul_f32 v[70:71], v[84:85], v[70:71]
	v_cvt_pk_bf16_f32 v68, v68, v69
	v_cvt_pk_bf16_f32 v69, v70, v71
	global_store_dwordx2 v[124:125], v[78:79], off
	global_store_dwordx2 v[124:125], v[80:81], off offset:512
	global_store_dwordx2 v[124:125], v[66:67], off offset:1024
	global_store_dwordx2 v[124:125], v[68:69], off offset:1536
	v_mul_f32_e32 v66, 0x45800000, v64
	v_cndmask_b32_e32 v64, v64, v66, vcc
	v_pk_mul_f32 v[66:67], v[102:103], v[64:65] op_sel_hi:[1,0]
	v_pk_mul_f32 v[68:69], v[104:105], v[64:65] op_sel_hi:[1,0]
	v_pk_mul_f32 v[66:67], v[110:111], v[66:67]
	v_pk_mul_f32 v[68:69], v[112:113], v[68:69]
	v_cvt_pk_bf16_f32 v66, v66, v67
	v_cvt_pk_bf16_f32 v67, v68, v69
	global_store_dwordx2 v[122:123], v[66:67], off
	v_pk_mul_f32 v[66:67], v[94:95], v[64:65] op_sel_hi:[1,0]
	v_pk_mul_f32 v[68:69], v[96:97], v[64:65] op_sel_hi:[1,0]
	v_pk_mul_f32 v[66:67], v[106:107], v[66:67]
	v_pk_mul_f32 v[68:69], v[108:109], v[68:69]
	v_cvt_pk_bf16_f32 v66, v66, v67
	v_cvt_pk_bf16_f32 v67, v68, v69
	global_store_dwordx2 v[122:123], v[66:67], off offset:512
	v_pk_mul_f32 v[66:67], v[90:91], v[64:65] op_sel_hi:[1,0]
	v_pk_mul_f32 v[68:69], v[92:93], v[64:65] op_sel_hi:[1,0]
	v_pk_mul_f32 v[66:67], v[98:99], v[66:67]
	v_pk_mul_f32 v[68:69], v[100:101], v[68:69]
	v_cvt_pk_bf16_f32 v66, v66, v67
	v_cvt_pk_bf16_f32 v67, v68, v69
	global_store_dwordx2 v[122:123], v[66:67], off offset:1024
	v_pk_mul_f32 v[66:67], v[74:75], v[64:65] op_sel_hi:[1,0]
	v_pk_mul_f32 v[68:69], v[76:77], v[64:65] op_sel_hi:[1,0]
	v_pk_mul_f32 v[66:67], v[82:83], v[66:67]
	v_pk_mul_f32 v[68:69], v[84:85], v[68:69]
	v_cvt_pk_bf16_f32 v66, v66, v67
	v_cvt_pk_bf16_f32 v67, v68, v69
	global_store_dwordx2 v[122:123], v[66:67], off offset:1536
	s_add_i32 s88, s88, 1

; DI bf16_t f2bf(float a) { return (bf16_t)(pack2(a, 0.f) & 0xffffu); }
; DI int tidx() { int t = threadIdx.x; asm volatile("" : "+v"(t)); return t; }
; DI int bidx() { int b = blockIdx.x; asm volatile("" : "+s"(b)); return b; }
; DI const float* IN(int i) { return *(const float* const __attribute__((address_space(4)))*)(KA() + 8 * i); }
; DI float* OUTP() { return *(float* const __attribute__((address_space(4)))*)(KA() + 8 * 29); }
; DI char* WS(const Params&) { return *(char* const __attribute__((address_space(4)))*)(KA() + 8 * 30); }
; DI void phase0(const Params& p, int l, char* smraw) {
;     ...
;   const float* xin = (l == 0) ? IN(0) : OUTP();
;   rmsnorm_rows(xin, IN(1) + l * 1024, (bf16_t*)(WS(p) + O_XN), nullptr);
;   const int gtid = bidx() * 512 + tidx(), nth = gridDim.x * 512;
;   if (l == 1) {
;     bf16_t* v1t = (bf16_t*)(WS(p) + O_V1T); bf16_t* v2t = (bf16_t*)(WS(p) + O_V2T);
;     const float* v1 = IN(22); const float* v2 = IN(23);
;     for (int idx = gtid; idx < 8192; idx += nth) {
;       { const int j = idx >> 8, c = idx & 255; v1t[idx] = f2bf(v1[c * 32 + j]); }
;       { const int c = idx >> 5, j = idx & 31; v2t[idx] = f2bf(v2[j * 256 + c]); }
;     }
.LBB0_145:
	v_readlane_b32 s6, v252, 6
	v_readlane_b32 s7, v252, 7
	s_mov_b64 s[4:5], s[6:7]
	v_mov_b32_e32 v0, v201
	s_waitcnt vmcnt(0)
	v_mov_b32_e32 v2, v201
	v_readlane_b32 s20, v252, 4
.LBB0_148:
	v_readlane_b32 s2, v252, 0
	v_readlane_b32 s40, v252, 4
	v_mov_b32_e32 v0, v201
	v_readlane_b32 s3, v252, 1
	s_load_dword s0, s[2:3], 0x10
	s_load_dword s1, s[2:3], 0x0
	v_lshl_add_u32 v2, s40, 9, v0
	s_waitcnt lgkmcnt(0)
	s_lshr_b32 s0, s0, 16
	s_cmp_lg_u32 s0, 0
	s_cselect_b64 s[2:3], -1, 0
	s_cmp_lg_u64 s[2:3], 0
	s_addc_u32 s10, s1, 0
	v_readlane_b32 s0, v252, 50
	v_readlane_b32 s1, v252, 51
	s_andn2_b64 vcc, exec, s[0:1]
	s_lshl_b32 s2, s10, 9
	s_cbranch_vccnz .LBB0_153
	v_readlane_b32 s20, v252, 6
	v_readlane_b32 s21, v252, 7
	s_movk_i32 s0, 0x2000
	s_mov_b64 s[34:35], s[20:21]
	s_mov_b64 s[22:23], s[20:21]
	s_mov_b64 s[6:7], s[20:21]
	v_cmp_gt_i32_e32 vcc, s0, v2
	s_and_saveexec_b64 s[4:5], vcc
	s_cbranch_execz .LBB0_152
	s_load_dwordx2 s[34:35], s[34:35], 0xf0
	s_nop 0
	s_load_dwordx2 s[36:37], s[22:23], 0xf0
	s_nop 0
	s_load_dwordx2 s[6:7], s[6:7], 0xb0
	s_nop 0
	s_load_dwordx2 s[20:21], s[20:21], 0xb8
	v_lshlrev_b32_e32 v3, 8, v0
	s_waitcnt lgkmcnt(0)
	s_add_u32 s22, s34, 0x1298400
	s_addc_u32 s23, s35, 0
	s_add_u32 s34, s36, 0x129c400
	v_lshl_add_u32 v6, s40, 17, v3
	v_ashrrev_i32_e32 v3, 31, v2
	s_addc_u32 s35, s37, 0
	v_lshlrev_b64 v[4:5], 1, v[2:3]
	s_ashr_i32 s3, s2, 31
	v_lshlrev_b32_e32 v3, 5, v0
	s_lshl_b32 s41, s10, 17
	s_lshl_b64 s[36:37], s[2:3], 1
	v_lshl_add_u32 v3, s40, 14, v3
	s_lshl_b32 s3, s10, 14
	s_mov_b64 s[38:39], 0
	v_mov_b32_e32 v7, v2
